# fox fast paths: 16-term row-sum trees as packed f32 adds (8 instructions instead of 15)
# speedup vs baseline: 1.0003x; 1.0003x over previous
; DI f32x4 mmaT(bf16x8 a_m, bf16x8 b_n, f32x4 c) { return __builtin_amdgcn_mfma_f32_16x16x32_bf16(b_n, a_m, c, 0, 0, 0); }
; DI v4i16_t tr_rd(const bf16_t* a) { return __builtin_amdgcn_ds_read_tr16_b64_v4i16((LDSP v4i16_t*)a); }
; template <bool DIAG>
; DI void fox_tile(const bf16_t* sK, const bf16_t* sV, const float* sFk, const bf16x8 (&qf)[2][2], f32x4 (&o)[2][4], float (&mrun)[2], float (&lsum)[2], int key0, int qg0, int fr, int fq, int lane) {
;   const float SC2 = 0.125f * LOG2E;
;   f32x4 s[2][4];
;   const int kof = (fr * 64 + fq * 16) ^ ((fr >> 3) << 5);
; #pragma unroll
;   for (int t = 0; t < 4; ++t) {
;     const bf16x8 k0 = *(const bf16x8*)((const unsigned char*)sK + (t * 2) * 1024 + kof), k1 = *(const bf16x8*)((const unsigned char*)sK + (t * 2 + 1) * 1024 + kof);
; #pragma unroll
;     for (int mi = 0; mi < 2; ++mi) { s[mi][t] = mmaT(qf[mi][0], k0, (f32x4){0.f, 0.f, 0.f, 0.f}); s[mi][t] = mmaT(qf[mi][1], k1, s[mi][t]); }
;   }
;   f32x4 fk[4];
; #pragma unroll
;   for (int t = 0; t < 4; ++t) fk[t] = *(const f32x4*)(sFk + 16 * t + 4 * fq);
;   __builtin_amdgcn_sched_barrier(0);
;   bf16x8 vf[2][4];
; #pragma unroll
;   for (int k2 = 0; k2 < 2; ++k2)
; #pragma unroll
;     for (int d = 0; d < 4; ++d) {
;       const bf16_t* a = sV + (32 * k2 + 4 * fq + (fr >> 2)) * 72 + 16 * d + 4 * (fr & 3);
;       const v4i16_t lo = tr_rd(a), hi = tr_rd(a + 16 * 72);
;       vf[k2][d] = __builtin_shufflevector(lo, hi, 0, 1, 2, 3, 4, 5, 6, 7);
;     }
;   __builtin_amdgcn_sched_barrier(0);
; #pragma unroll
;   for (int mi = 0; mi < 2; ++mi) {
;     float mx = -INFINITY;
; #pragma unroll
;     for (int t = 0; t < 4; ++t)
; #pragma unroll
;       for (int j = 0; j < 4; ++j) {
;         float x = __builtin_fmaf(s[mi][t][j], SC2, fk[t][j]);
;         if (DIAG) { if (key0 + 16 * t + 4 * fq + j > qg0 + 16 * mi) x = -INFINITY; }
;         s[mi][t][j] = x; mx = fmaxf(mx, x);
.LBB0_489:
	s_mul_i32 s4, s21, 0x4900
	s_add_i32 s4, s4, 32
	v_add_u32_e32 v24, s4, v213
	ds_read_b128 v[64:67], v24
	ds_read_b128 v[68:71], v24 offset:1024
	ds_read_b128 v[56:59], v24 offset:2048
	ds_read_b128 v[60:63], v24 offset:3072
	ds_read_b128 v[48:51], v24 offset:4096
	ds_read_b128 v[52:55], v24 offset:5120
	ds_read_b128 v[40:43], v24 offset:6144
	ds_read_b128 v[44:47], v24 offset:7168
	v_lshl_add_u32 v24, v209, 2, s4
	ds_read_b128 v[36:39], v24 offset:18432
	ds_read_b128 v[32:35], v24 offset:18496
	ds_read_b128 v[28:31], v24 offset:18560
	ds_read_b128 v[24:27], v24 offset:18624
	v_lshl_add_u32 v72, v214, 1, s4
	v_readfirstlane_b32 s100, v212
	s_add_i32 s101, s18, 94
	s_mov_b64 s[4:5], -1
	v_add_u32_e32 v221, v72, v215
	s_cmp_le_i32 s101, s100
	s_cbranch_scc1 .LBB0_491
	s_cmp_eq_u32 s98, 0
	s_cbranch_scc1 .Lfox1_dslow
	s_waitcnt lgkmcnt(11)
	v_mfma_f32_16x16x32_bf16 v[72:75], v[64:67], v[0:3], v[224:227]
	s_waitcnt lgkmcnt(10)
	v_mfma_f32_16x16x32_bf16 v[72:75], v[68:71], v[4:7], v[72:75]
	s_waitcnt lgkmcnt(9)
	v_mfma_f32_16x16x32_bf16 v[76:79], v[56:59], v[0:3], v[224:227]
	s_waitcnt lgkmcnt(8)
	v_mfma_f32_16x16x32_bf16 v[76:79], v[60:63], v[4:7], v[76:79]
	s_waitcnt lgkmcnt(7)
	v_mfma_f32_16x16x32_bf16 v[80:83], v[48:51], v[0:3], v[224:227]
	s_waitcnt lgkmcnt(6)
	v_mfma_f32_16x16x32_bf16 v[80:83], v[52:55], v[4:7], v[80:83]
	s_waitcnt lgkmcnt(5)
	v_mfma_f32_16x16x32_bf16 v[96:99], v[40:43], v[0:3], v[224:227]
	s_waitcnt lgkmcnt(4)
	v_mfma_f32_16x16x32_bf16 v[96:99], v[44:47], v[4:7], v[96:99]
	s_waitcnt lgkmcnt(0)
	v_add_u32_e32 v172, s18, v209
	v_sub_u32_e32 v172, v172, v206
	v_add_u32_e32 v176, -16, v172
	v_add_u32_e32 v173, 16, v172
	v_add_u32_e32 v177, 16, v176
	v_add_u32_e32 v174, 32, v172
	v_add_u32_e32 v178, 32, v176
	v_add_u32_e32 v175, 48, v172
	v_add_u32_e32 v179, 48, v176
	v_mfma_f32_16x16x32_bf16 v[84:87], v[64:67], v[8:11], v[228:231]
	v_mfma_f32_16x16x32_bf16 v[84:87], v[68:71], v[12:15], v[84:87]
	v_fmamk_f32 v72, v72, 0x3e38aa3b, v36
	v_fmamk_f32 v73, v73, 0x3e38aa3b, v37
	v_fmamk_f32 v74, v74, 0x3e38aa3b, v38
	v_fmamk_f32 v75, v75, 0x3e38aa3b, v39
	v_mfma_f32_16x16x32_bf16 v[88:91], v[56:59], v[8:11], v[228:231]
	v_mfma_f32_16x16x32_bf16 v[88:91], v[60:63], v[12:15], v[88:91]
	v_fmamk_f32 v76, v76, 0x3e38aa3b, v32
	v_fmamk_f32 v77, v77, 0x3e38aa3b, v33
	v_fmamk_f32 v78, v78, 0x3e38aa3b, v34
	v_fmamk_f32 v79, v79, 0x3e38aa3b, v35
	v_mfma_f32_16x16x32_bf16 v[92:95], v[48:51], v[8:11], v[228:231]
	v_mfma_f32_16x16x32_bf16 v[92:95], v[52:55], v[12:15], v[92:95]
	v_fmamk_f32 v80, v80, 0x3e38aa3b, v28
	v_fmamk_f32 v81, v81, 0x3e38aa3b, v29
	v_fmamk_f32 v82, v82, 0x3e38aa3b, v30
	v_fmamk_f32 v83, v83, 0x3e38aa3b, v31
	v_mfma_f32_16x16x32_bf16 v[164:167], v[40:43], v[8:11], v[228:231]
	v_mfma_f32_16x16x32_bf16 v[164:167], v[44:47], v[12:15], v[164:167]
	v_fmamk_f32 v96, v96, 0x3e38aa3b, v24
	v_fmamk_f32 v97, v97, 0x3e38aa3b, v25
	v_fmamk_f32 v98, v98, 0x3e38aa3b, v26
	v_fmamk_f32 v99, v99, 0x3e38aa3b, v27
	ds_read_b64_tr_b16 v[68:69], v221 offset:9216
	ds_read_b64_tr_b16 v[60:61], v221 offset:9248
	ds_read_b64_tr_b16 v[64:65], v221 offset:9280
	ds_read_b64_tr_b16 v[56:57], v221 offset:9312
	ds_read_b64_tr_b16 v[70:71], v221 offset:11520
	ds_read_b64_tr_b16 v[62:63], v221 offset:11552
	ds_read_b64_tr_b16 v[66:67], v221 offset:11584
	ds_read_b64_tr_b16 v[58:59], v221 offset:11616
	ds_read_b64_tr_b16 v[52:53], v221 offset:13824
	ds_read_b64_tr_b16 v[48:49], v221 offset:13856
	ds_read_b64_tr_b16 v[44:45], v221 offset:13888
	ds_read_b64_tr_b16 v[40:41], v221 offset:13920
	ds_read_b64_tr_b16 v[54:55], v221 offset:16128
	ds_read_b64_tr_b16 v[50:51], v221 offset:16160
	ds_read_b64_tr_b16 v[46:47], v221 offset:16192
	ds_read_b64_tr_b16 v[42:43], v221 offset:16224
	v_cmp_ge_i32_e32 vcc, 0, v172
	v_cmp_ge_i32_e64 s[4:5], -1, v172
	v_cmp_ge_i32_e64 s[100:101], -2, v172
	v_cndmask_b32_e32 v72, v200, v72, vcc
	v_cndmask_b32_e64 v73, v200, v73, s[4:5]
	v_cndmask_b32_e64 v74, v200, v74, s[100:101]
	v_cmp_ge_i32_e32 vcc, -3, v172
	v_cmp_ge_i32_e64 s[4:5], 0, v173
	v_cmp_ge_i32_e64 s[100:101], -1, v173
	v_cndmask_b32_e32 v75, v200, v75, vcc
	v_cndmask_b32_e64 v76, v200, v76, s[4:5]
	v_cndmask_b32_e64 v77, v200, v77, s[100:101]
	v_cmp_ge_i32_e32 vcc, -2, v173
	v_cmp_ge_i32_e64 s[4:5], -3, v173
	v_cmp_ge_i32_e64 s[100:101], 0, v174
	v_cndmask_b32_e32 v78, v200, v78, vcc
	v_cndmask_b32_e64 v79, v200, v79, s[4:5]
	v_cndmask_b32_e64 v80, v200, v80, s[100:101]
; DI unsigned pk2(float lo, float hi) { unsigned r; asm volatile("v_cvt_pk_bf16_f32 %0, %1, %2" : "=v"(r) : "v"(lo), "v"(hi)); return r; }
; DI float ex2(float x) { return __builtin_amdgcn_exp2f(x); }
; DI float shx(float v, int m, int lane) { return __int_as_float(__builtin_amdgcn_ds_bpermute((lane ^ m) << 2, __float_as_int(v))); }
; template <bool DIAG>
; DI void fox_tile(const bf16_t* sK, const bf16_t* sV, const float* sFk, const bf16x8 (&qf)[2][2], f32x4 (&o)[2][4], float (&mrun)[2], float (&lsum)[2], int key0, int qg0, int fr, int fq, int lane) {
;     ...
;         float x = __builtin_fmaf(s[mi][t][j], SC2, fk[t][j]);
;         if (DIAG) { if (key0 + 16 * t + 4 * fq + j > qg0 + 16 * mi) x = -INFINITY; }
;         s[mi][t][j] = x; mx = fmaxf(mx, x);
;       }
;     mx = fmaxf(mx, shx(mx, 16, lane)); mx = fmaxf(mx, shx(mx, 32, lane));
;     const float mnew = fmaxf(mrun[mi], mx), alpha = ex2(mrun[mi] - mnew);
;     mrun[mi] = mnew;
;     float ps = 0.f;
; #pragma unroll
;     for (int t = 0; t < 4; ++t)
; #pragma unroll
;       for (int j = 0; j < 4; ++j) { const float pv = ex2(s[mi][t][j] - mnew); s[mi][t][j] = pv; ps += pv; }
;     lsum[mi] = lsum[mi] * alpha + ps;
; #pragma unroll
;     for (int d = 0; d < 4; ++d) o[mi][d] *= alpha;
;   }
; #pragma unroll
;   for (int k2 = 0; k2 < 2; ++k2) {
;     bf16x8 pa[2];
; #pragma unroll
;     for (int mi = 0; mi < 2; ++mi) pa[mi] = mk8(pk2(s[mi][2 * k2][0], s[mi][2 * k2][1]), pk2(s[mi][2 * k2][2], s[mi][2 * k2][3]), pk2(s[mi][2 * k2 + 1][0], s[mi][2 * k2 + 1][1]), pk2(s[mi][2 * k2 + 1][2], s[mi][2 * k2 + 1][3]));
	v_cmp_ge_i32_e32 vcc, -1, v174
	v_cmp_ge_i32_e64 s[4:5], -2, v174
	v_cmp_ge_i32_e64 s[100:101], -3, v174
	v_cndmask_b32_e32 v81, v200, v81, vcc
	v_cndmask_b32_e64 v82, v200, v82, s[4:5]
	v_cndmask_b32_e64 v83, v200, v83, s[100:101]
	v_cmp_ge_i32_e32 vcc, 0, v175
	v_cmp_ge_i32_e64 s[4:5], -1, v175
	v_cmp_ge_i32_e64 s[100:101], -2, v175
	v_cndmask_b32_e32 v96, v200, v96, vcc
	v_cndmask_b32_e64 v97, v200, v97, s[4:5]
	v_cndmask_b32_e64 v98, v200, v98, s[100:101]
	v_cmp_ge_i32_e32 vcc, -3, v175
	s_nop 1
	v_cndmask_b32_e32 v99, v200, v99, vcc
	v_exp_f32_e32 v72, v72
	v_exp_f32_e32 v73, v73
	v_exp_f32_e32 v74, v74
	v_exp_f32_e32 v75, v75
	v_exp_f32_e32 v76, v76
	v_exp_f32_e32 v77, v77
	v_exp_f32_e32 v78, v78
	v_exp_f32_e32 v79, v79
	v_exp_f32_e32 v80, v80
	v_exp_f32_e32 v81, v81
	v_exp_f32_e32 v82, v82
	v_exp_f32_e32 v83, v83
	v_exp_f32_e32 v96, v96
	v_exp_f32_e32 v97, v97
	v_exp_f32_e32 v98, v98
	v_exp_f32_e32 v99, v99
	v_fmamk_f32 v84, v84, 0x3e38aa3b, v36
	v_fmamk_f32 v85, v85, 0x3e38aa3b, v37
	v_fmamk_f32 v86, v86, 0x3e38aa3b, v38
	v_fmamk_f32 v87, v87, 0x3e38aa3b, v39
	v_fmamk_f32 v88, v88, 0x3e38aa3b, v32
	v_fmamk_f32 v89, v89, 0x3e38aa3b, v33
	v_fmamk_f32 v90, v90, 0x3e38aa3b, v34
	v_fmamk_f32 v91, v91, 0x3e38aa3b, v35
	v_fmamk_f32 v92, v92, 0x3e38aa3b, v28
	v_fmamk_f32 v93, v93, 0x3e38aa3b, v29
	v_fmamk_f32 v94, v94, 0x3e38aa3b, v30
	v_fmamk_f32 v95, v95, 0x3e38aa3b, v31
	v_fmamk_f32 v164, v164, 0x3e38aa3b, v24
	v_fmamk_f32 v165, v165, 0x3e38aa3b, v25
	v_fmamk_f32 v166, v166, 0x3e38aa3b, v26
	v_fmamk_f32 v167, v167, 0x3e38aa3b, v27
	v_cmp_ge_i32_e32 vcc, 0, v176
	v_cmp_ge_i32_e64 s[4:5], -1, v176
	v_cmp_ge_i32_e64 s[100:101], -2, v176
	v_cndmask_b32_e32 v84, v200, v84, vcc
	v_cndmask_b32_e64 v85, v200, v85, s[4:5]
	v_cndmask_b32_e64 v86, v200, v86, s[100:101]
	v_cmp_ge_i32_e32 vcc, -3, v176
	v_cmp_ge_i32_e64 s[4:5], 0, v177
	v_cmp_ge_i32_e64 s[100:101], -1, v177
	v_cndmask_b32_e32 v87, v200, v87, vcc
	v_cndmask_b32_e64 v88, v200, v88, s[4:5]
	v_cndmask_b32_e64 v89, v200, v89, s[100:101]
	v_cmp_ge_i32_e32 vcc, -2, v177
	v_cmp_ge_i32_e64 s[4:5], -3, v177
	v_cmp_ge_i32_e64 s[100:101], 0, v178
	v_cndmask_b32_e32 v90, v200, v90, vcc
	v_cndmask_b32_e64 v91, v200, v91, s[4:5]
	v_cndmask_b32_e64 v92, v200, v92, s[100:101]
	v_cmp_ge_i32_e32 vcc, -1, v178
	v_cmp_ge_i32_e64 s[4:5], -2, v178
	v_cmp_ge_i32_e64 s[100:101], -3, v178
	v_cndmask_b32_e32 v93, v200, v93, vcc
	v_cndmask_b32_e64 v94, v200, v94, s[4:5]
	v_cndmask_b32_e64 v95, v200, v95, s[100:101]
	v_cmp_ge_i32_e32 vcc, 0, v179
	v_cmp_ge_i32_e64 s[4:5], -1, v179
	v_cmp_ge_i32_e64 s[100:101], -2, v179
	v_cndmask_b32_e32 v164, v200, v164, vcc
	v_cndmask_b32_e64 v165, v200, v165, s[4:5]
	v_cndmask_b32_e64 v166, v200, v166, s[100:101]
	v_cmp_ge_i32_e32 vcc, -3, v179
	s_nop 1
	v_cndmask_b32_e32 v167, v200, v167, vcc
	v_pk_add_f32 v[146:147], v[72:73], v[74:75]
	v_pk_add_f32 v[148:149], v[76:77], v[78:79]
	v_pk_add_f32 v[150:151], v[80:81], v[82:83]
	v_pk_add_f32 v[152:153], v[96:97], v[98:99]
	v_pk_add_f32 v[146:147], v[146:147], v[148:149]
	v_pk_add_f32 v[150:151], v[150:151], v[152:153]
	v_pk_add_f32 v[146:147], v[146:147], v[150:151]
	v_add_f32_e32 v146, v146, v147
	v_exp_f32_e32 v84, v84
	v_exp_f32_e32 v85, v85
	v_exp_f32_e32 v86, v86
	v_exp_f32_e32 v87, v87
	v_exp_f32_e32 v88, v88
	v_exp_f32_e32 v89, v89
	v_exp_f32_e32 v90, v90
	v_exp_f32_e32 v91, v91
	v_exp_f32_e32 v92, v92
	v_exp_f32_e32 v93, v93
	v_exp_f32_e32 v94, v94
	v_exp_f32_e32 v95, v95
	v_exp_f32_e32 v164, v164
	v_exp_f32_e32 v165, v165
	v_exp_f32_e32 v166, v166
	v_exp_f32_e32 v167, v167
	v_pk_add_f32 v[148:149], v[84:85], v[86:87]
	v_pk_add_f32 v[150:151], v[88:89], v[90:91]
	v_pk_add_f32 v[152:153], v[92:93], v[94:95]
	v_pk_add_f32 v[154:155], v[164:165], v[166:167]
	v_pk_add_f32 v[148:149], v[148:149], v[150:151]
	v_pk_add_f32 v[152:153], v[152:153], v[154:155]
	v_pk_add_f32 v[148:149], v[148:149], v[152:153]
	v_add_f32_e32 v148, v148, v149
	v_max_f32_e32 v147, v146, v148
	v_cmp_lt_f32_e32 vcc, 0x69800000, v147
	s_cbranch_vccnz .Lfox1_dfallback
	v_add_f32_e32 v128, v128, v146
	v_add_f32_e32 v129, v129, v148
	v_cvt_pk_bf16_f32 v36, v72, v73
	v_cvt_pk_bf16_f32 v37, v74, v75
	v_cvt_pk_bf16_f32 v38, v76, v77
	v_cvt_pk_bf16_f32 v39, v78, v79
	v_cvt_pk_bf16_f32 v28, v80, v81
	v_cvt_pk_bf16_f32 v29, v82, v83
	v_cvt_pk_bf16_f32 v30, v96, v97
	v_cvt_pk_bf16_f32 v31, v98, v99
	s_cmp_eq_u32 s99, 0
	s_cbranch_scc1 .Lfox1_nm4
	s_barrier

; template <bool DIAG>
; DI void fox_tile(const bf16_t* sK, const bf16_t* sV, const float* sFk, const bf16x8 (&qf)[2][2], f32x4 (&o)[2][4], float (&mrun)[2], float (&lsum)[2], int key0, int qg0, int fr, int fq, int lane) {
;     ...
; #pragma unroll
;   for (int t = 0; t < 4; ++t) {
;     const bf16x8 k0 = *(const bf16x8*)((const unsigned char*)sK + (t * 2) * 1024 + kof), k1 = *(const bf16x8*)((const unsigned char*)sK + (t * 2 + 1) * 1024 + kof);
; #pragma unroll
;     for (int mi = 0; mi < 2; ++mi) { s[mi][t] = mmaT(qf[mi][0], k0, (f32x4){0.f, 0.f, 0.f, 0.f}); s[mi][t] = mmaT(qf[mi][1], k1, s[mi][t]); }
;   }
;   f32x4 fk[4];
; #pragma unroll
;   for (int t = 0; t < 4; ++t) fk[t] = *(const f32x4*)(sFk + 16 * t + 4 * fq);
;   __builtin_amdgcn_sched_barrier(0);
;   bf16x8 vf[2][4];
; #pragma unroll
;   for (int k2 = 0; k2 < 2; ++k2)
; #pragma unroll
;     for (int d = 0; d < 4; ++d) {
;       const bf16_t* a = sV + (32 * k2 + 4 * fq + (fr >> 2)) * 72 + 16 * d + 4 * (fr & 3);
;       const v4i16_t lo = tr_rd(a), hi = tr_rd(a + 16 * 72);
;       vf[k2][d] = __builtin_shufflevector(lo, hi, 0, 1, 2, 3, 4, 5, 6, 7);
;     }
;   __builtin_amdgcn_sched_barrier(0);
; #pragma unroll
;   for (int mi = 0; mi < 2; ++mi) {
;     float mx = -INFINITY;
; #pragma unroll
;     for (int t = 0; t < 4; ++t)
; #pragma unroll
;       for (int j = 0; j < 4; ++j) {
;         float x = __builtin_fmaf(s[mi][t][j], SC2, fk[t][j]);
;         if (DIAG) { if (key0 + 16 * t + 4 * fq + j > qg0 + 16 * mi) x = -INFINITY; }
;         s[mi][t][j] = x; mx = fmaxf(mx, x);
;       }
;     mx = fmaxf(mx, shx(mx, 16, lane)); mx = fmaxf(mx, shx(mx, 32, lane));
;     const float mnew = fmaxf(mrun[mi], mx), alpha = ex2(mrun[mi] - mnew);
;     mrun[mi] = mnew;
;     float ps = 0.f;
; #pragma unroll
;     for (int t = 0; t < 4; ++t)
; #pragma unroll
;       for (int j = 0; j < 4; ++j) { const float pv = ex2(s[mi][t][j] - mnew); s[mi][t][j] = pv; ps += pv; }
;     lsum[mi] = lsum[mi] * alpha + ps;
; #pragma unroll
;     for (int d = 0; d < 4; ++d) o[mi][d] *= alpha;
;   }
; #pragma unroll
;   for (int k2 = 0; k2 < 2; ++k2) {
;     bf16x8 pa[2];
; #pragma unroll
;     for (int mi = 0; mi < 2; ++mi) pa[mi] = mk8(pk2(s[mi][2 * k2][0], s[mi][2 * k2][1]), pk2(s[mi][2 * k2][2], s[mi][2 * k2][3]), pk2(s[mi][2 * k2 + 1][0], s[mi][2 * k2 + 1][1]), pk2(s[mi][2 * k2 + 1][2], s[mi][2 * k2 + 1][3]));
.LBB0_491:
	s_andn2_b64 vcc, exec, s[4:5]
	s_cbranch_vccnz .LBB0_493
	s_cmp_eq_u32 s98, 0
	s_cbranch_scc1 .Lfox1_slow
	s_waitcnt lgkmcnt(11)
	v_mfma_f32_16x16x32_bf16 v[72:75], v[64:67], v[0:3], v[224:227]
	s_waitcnt lgkmcnt(10)
	v_mfma_f32_16x16x32_bf16 v[72:75], v[68:71], v[4:7], v[72:75]
	s_waitcnt lgkmcnt(9)
	v_mfma_f32_16x16x32_bf16 v[76:79], v[56:59], v[0:3], v[224:227]
	s_waitcnt lgkmcnt(8)
	v_mfma_f32_16x16x32_bf16 v[76:79], v[60:63], v[4:7], v[76:79]
	s_waitcnt lgkmcnt(7)
	v_mfma_f32_16x16x32_bf16 v[80:83], v[48:51], v[0:3], v[224:227]
	s_waitcnt lgkmcnt(6)
	v_mfma_f32_16x16x32_bf16 v[80:83], v[52:55], v[4:7], v[80:83]
	s_waitcnt lgkmcnt(5)
	v_mfma_f32_16x16x32_bf16 v[96:99], v[40:43], v[0:3], v[224:227]
	s_waitcnt lgkmcnt(4)
	v_mfma_f32_16x16x32_bf16 v[96:99], v[44:47], v[4:7], v[96:99]
	s_waitcnt lgkmcnt(0)
	v_mfma_f32_16x16x32_bf16 v[84:87], v[64:67], v[8:11], v[228:231]
	v_mfma_f32_16x16x32_bf16 v[84:87], v[68:71], v[12:15], v[84:87]
	v_fmamk_f32 v72, v72, 0x3e38aa3b, v36
	v_fmamk_f32 v73, v73, 0x3e38aa3b, v37
	v_fmamk_f32 v74, v74, 0x3e38aa3b, v38
	v_fmamk_f32 v75, v75, 0x3e38aa3b, v39
	v_mfma_f32_16x16x32_bf16 v[88:91], v[56:59], v[8:11], v[228:231]
	v_mfma_f32_16x16x32_bf16 v[88:91], v[60:63], v[12:15], v[88:91]
	v_fmamk_f32 v76, v76, 0x3e38aa3b, v32
	v_fmamk_f32 v77, v77, 0x3e38aa3b, v33
	v_fmamk_f32 v78, v78, 0x3e38aa3b, v34
	v_fmamk_f32 v79, v79, 0x3e38aa3b, v35
	v_mfma_f32_16x16x32_bf16 v[92:95], v[48:51], v[8:11], v[228:231]
	v_mfma_f32_16x16x32_bf16 v[92:95], v[52:55], v[12:15], v[92:95]
	v_fmamk_f32 v80, v80, 0x3e38aa3b, v28
	v_fmamk_f32 v81, v81, 0x3e38aa3b, v29
	v_fmamk_f32 v82, v82, 0x3e38aa3b, v30
	v_fmamk_f32 v83, v83, 0x3e38aa3b, v31
	v_mfma_f32_16x16x32_bf16 v[164:167], v[40:43], v[8:11], v[228:231]
	v_mfma_f32_16x16x32_bf16 v[164:167], v[44:47], v[12:15], v[164:167]
	v_fmamk_f32 v96, v96, 0x3e38aa3b, v24
	v_fmamk_f32 v97, v97, 0x3e38aa3b, v25
	v_fmamk_f32 v98, v98, 0x3e38aa3b, v26
	v_fmamk_f32 v99, v99, 0x3e38aa3b, v27
	ds_read_b64_tr_b16 v[68:69], v221 offset:9216
	ds_read_b64_tr_b16 v[60:61], v221 offset:9248
	ds_read_b64_tr_b16 v[64:65], v221 offset:9280
	ds_read_b64_tr_b16 v[56:57], v221 offset:9312
	ds_read_b64_tr_b16 v[70:71], v221 offset:11520
	ds_read_b64_tr_b16 v[62:63], v221 offset:11552
	ds_read_b64_tr_b16 v[66:67], v221 offset:11584
	ds_read_b64_tr_b16 v[58:59], v221 offset:11616
	ds_read_b64_tr_b16 v[52:53], v221 offset:13824
	ds_read_b64_tr_b16 v[48:49], v221 offset:13856
	ds_read_b64_tr_b16 v[44:45], v221 offset:13888
	ds_read_b64_tr_b16 v[40:41], v221 offset:13920
	ds_read_b64_tr_b16 v[54:55], v221 offset:16128
	ds_read_b64_tr_b16 v[50:51], v221 offset:16160
	ds_read_b64_tr_b16 v[46:47], v221 offset:16192
	ds_read_b64_tr_b16 v[42:43], v221 offset:16224
	v_exp_f32_e32 v72, v72
	v_exp_f32_e32 v73, v73
	v_exp_f32_e32 v74, v74
	v_exp_f32_e32 v75, v75
	v_exp_f32_e32 v76, v76
	v_exp_f32_e32 v77, v77
	v_exp_f32_e32 v78, v78
	v_exp_f32_e32 v79, v79
	v_exp_f32_e32 v80, v80
	v_exp_f32_e32 v81, v81
	v_exp_f32_e32 v82, v82
	v_exp_f32_e32 v83, v83
	v_exp_f32_e32 v96, v96
	v_exp_f32_e32 v97, v97
	v_exp_f32_e32 v98, v98
	v_exp_f32_e32 v99, v99
	v_fmamk_f32 v84, v84, 0x3e38aa3b, v36
	v_fmamk_f32 v85, v85, 0x3e38aa3b, v37
	v_fmamk_f32 v86, v86, 0x3e38aa3b, v38
	v_fmamk_f32 v87, v87, 0x3e38aa3b, v39
	v_fmamk_f32 v88, v88, 0x3e38aa3b, v32
	v_fmamk_f32 v89, v89, 0x3e38aa3b, v33
	v_fmamk_f32 v90, v90, 0x3e38aa3b, v34
	v_fmamk_f32 v91, v91, 0x3e38aa3b, v35
	v_fmamk_f32 v92, v92, 0x3e38aa3b, v28
	v_fmamk_f32 v93, v93, 0x3e38aa3b, v29
	v_fmamk_f32 v94, v94, 0x3e38aa3b, v30
	v_fmamk_f32 v95, v95, 0x3e38aa3b, v31
	v_fmamk_f32 v164, v164, 0x3e38aa3b, v24
	v_fmamk_f32 v165, v165, 0x3e38aa3b, v25
	v_fmamk_f32 v166, v166, 0x3e38aa3b, v26
	v_fmamk_f32 v167, v167, 0x3e38aa3b, v27
	v_pk_add_f32 v[146:147], v[72:73], v[74:75]
	v_pk_add_f32 v[148:149], v[76:77], v[78:79]
	v_pk_add_f32 v[150:151], v[80:81], v[82:83]
	v_pk_add_f32 v[152:153], v[96:97], v[98:99]
	v_pk_add_f32 v[146:147], v[146:147], v[148:149]
	v_pk_add_f32 v[150:151], v[150:151], v[152:153]
	v_pk_add_f32 v[146:147], v[146:147], v[150:151]
	v_add_f32_e32 v146, v146, v147
	v_exp_f32_e32 v84, v84
	v_exp_f32_e32 v85, v85
	v_exp_f32_e32 v86, v86
	v_exp_f32_e32 v87, v87
	v_exp_f32_e32 v88, v88
	v_exp_f32_e32 v89, v89
	v_exp_f32_e32 v90, v90
	v_exp_f32_e32 v91, v91
	v_exp_f32_e32 v92, v92
	v_exp_f32_e32 v93, v93
	v_exp_f32_e32 v94, v94
	v_exp_f32_e32 v95, v95
	v_exp_f32_e32 v164, v164
	v_exp_f32_e32 v165, v165
	v_exp_f32_e32 v166, v166
	v_exp_f32_e32 v167, v167
	v_pk_add_f32 v[148:149], v[84:85], v[86:87]
	v_pk_add_f32 v[150:151], v[88:89], v[90:91]
	v_pk_add_f32 v[152:153], v[92:93], v[94:95]
	v_pk_add_f32 v[154:155], v[164:165], v[166:167]
	v_pk_add_f32 v[148:149], v[148:149], v[150:151]
	v_pk_add_f32 v[152:153], v[152:153], v[154:155]
	v_pk_add_f32 v[148:149], v[148:149], v[152:153]
	v_add_f32_e32 v148, v148, v149
	v_max_f32_e32 v147, v146, v148
	v_cmp_lt_f32_e32 vcc, 0x69800000, v147
	s_cbranch_vccnz .Lfox1_fallback
	v_add_f32_e32 v128, v128, v146
	v_add_f32_e32 v129, v129, v148
	v_cvt_pk_bf16_f32 v36, v72, v73
	v_cvt_pk_bf16_f32 v37, v74, v75
	v_cvt_pk_bf16_f32 v38, v76, v77
	v_cvt_pk_bf16_f32 v39, v78, v79
	v_cvt_pk_bf16_f32 v28, v80, v81
	v_cvt_pk_bf16_f32 v29, v82, v83
	v_cvt_pk_bf16_f32 v30, v96, v97
	v_cvt_pk_bf16_f32 v31, v98, v99
	s_cmp_eq_u32 s99, 0
	s_cbranch_scc1 .Lfox1_nm2
	s_barrier

; DI f32x4 mmaT(bf16x8 a_m, bf16x8 b_n, f32x4 c) { return __builtin_amdgcn_mfma_f32_16x16x32_bf16(b_n, a_m, c, 0, 0, 0); }
; DI v4i16_t tr_rd(const bf16_t* a) { return __builtin_amdgcn_ds_read_tr16_b64_v4i16((LDSP v4i16_t*)a); }
; template <bool DIAG>
; DI void fox_tile(const bf16_t* sK, const bf16_t* sV, const float* sFk, const bf16x8 (&qf)[2][2], f32x4 (&o)[2][4], float (&mrun)[2], float (&lsum)[2], int key0, int qg0, int fr, int fq, int lane) {
;   const float SC2 = 0.125f * LOG2E;
;   f32x4 s[2][4];
;   const int kof = (fr * 64 + fq * 16) ^ ((fr >> 3) << 5);
; #pragma unroll
;   for (int t = 0; t < 4; ++t) {
;     const bf16x8 k0 = *(const bf16x8*)((const unsigned char*)sK + (t * 2) * 1024 + kof), k1 = *(const bf16x8*)((const unsigned char*)sK + (t * 2 + 1) * 1024 + kof);
; #pragma unroll
;     for (int mi = 0; mi < 2; ++mi) { s[mi][t] = mmaT(qf[mi][0], k0, (f32x4){0.f, 0.f, 0.f, 0.f}); s[mi][t] = mmaT(qf[mi][1], k1, s[mi][t]); }
;   }
;   f32x4 fk[4];
; #pragma unroll
;   for (int t = 0; t < 4; ++t) fk[t] = *(const f32x4*)(sFk + 16 * t + 4 * fq);
;   __builtin_amdgcn_sched_barrier(0);
;   bf16x8 vf[2][4];
; #pragma unroll
;   for (int k2 = 0; k2 < 2; ++k2)
; #pragma unroll
;     for (int d = 0; d < 4; ++d) {
;       const bf16_t* a = sV + (32 * k2 + 4 * fq + (fr >> 2)) * 72 + 16 * d + 4 * (fr & 3);
;       const v4i16_t lo = tr_rd(a), hi = tr_rd(a + 16 * 72);
;       vf[k2][d] = __builtin_shufflevector(lo, hi, 0, 1, 2, 3, 4, 5, 6, 7);
;     }
;   __builtin_amdgcn_sched_barrier(0);
; #pragma unroll
;   for (int mi = 0; mi < 2; ++mi) {
;     float mx = -INFINITY;
; #pragma unroll
;     for (int t = 0; t < 4; ++t)
; #pragma unroll
;       for (int j = 0; j < 4; ++j) {
;         float x = __builtin_fmaf(s[mi][t][j], SC2, fk[t][j]);
;         if (DIAG) { if (key0 + 16 * t + 4 * fq + j > qg0 + 16 * mi) x = -INFINITY; }
;         s[mi][t][j] = x; mx = fmaxf(mx, x);
.LBB0_609:
	s_mul_i32 s4, s20, 0x4900
	s_add_i32 s4, s4, 32
	v_add_u32_e32 v24, s4, v213
	ds_read_b128 v[64:67], v24
	ds_read_b128 v[68:71], v24 offset:1024
	ds_read_b128 v[56:59], v24 offset:2048
	ds_read_b128 v[60:63], v24 offset:3072
	ds_read_b128 v[48:51], v24 offset:4096
	ds_read_b128 v[52:55], v24 offset:5120
	ds_read_b128 v[40:43], v24 offset:6144
	ds_read_b128 v[44:47], v24 offset:7168
	v_lshl_add_u32 v24, v209, 2, s4
	ds_read_b128 v[36:39], v24 offset:18432
	ds_read_b128 v[32:35], v24 offset:18496
	ds_read_b128 v[28:31], v24 offset:18560
	ds_read_b128 v[24:27], v24 offset:18624
	v_lshl_add_u32 v72, v214, 1, s4
	v_readfirstlane_b32 s100, v212
	s_add_i32 s101, s17, 94
	s_mov_b64 s[4:5], -1
	v_add_u32_e32 v221, v72, v215
	s_cmp_le_i32 s101, s100
	s_cbranch_scc1 .LBB0_611
	s_cmp_eq_u32 s98, 0
	s_cbranch_scc1 .Lfox2_dslow
	s_waitcnt lgkmcnt(11)
	v_mfma_f32_16x16x32_bf16 v[72:75], v[64:67], v[0:3], v[224:227]
	s_waitcnt lgkmcnt(10)
	v_mfma_f32_16x16x32_bf16 v[72:75], v[68:71], v[4:7], v[72:75]
	s_waitcnt lgkmcnt(9)
	v_mfma_f32_16x16x32_bf16 v[76:79], v[56:59], v[0:3], v[224:227]
	s_waitcnt lgkmcnt(8)
	v_mfma_f32_16x16x32_bf16 v[76:79], v[60:63], v[4:7], v[76:79]
	s_waitcnt lgkmcnt(7)
	v_mfma_f32_16x16x32_bf16 v[80:83], v[48:51], v[0:3], v[224:227]
	s_waitcnt lgkmcnt(6)
	v_mfma_f32_16x16x32_bf16 v[80:83], v[52:55], v[4:7], v[80:83]
	s_waitcnt lgkmcnt(5)
	v_mfma_f32_16x16x32_bf16 v[96:99], v[40:43], v[0:3], v[224:227]
	s_waitcnt lgkmcnt(4)
	v_mfma_f32_16x16x32_bf16 v[96:99], v[44:47], v[4:7], v[96:99]
	s_waitcnt lgkmcnt(0)
	v_add_u32_e32 v172, s17, v209
	v_sub_u32_e32 v172, v172, v206
	v_add_u32_e32 v176, -16, v172
	v_add_u32_e32 v173, 16, v172
	v_add_u32_e32 v177, 16, v176
	v_add_u32_e32 v174, 32, v172
	v_add_u32_e32 v178, 32, v176
	v_add_u32_e32 v175, 48, v172
	v_add_u32_e32 v179, 48, v176
	v_mfma_f32_16x16x32_bf16 v[84:87], v[64:67], v[8:11], v[228:231]
	v_mfma_f32_16x16x32_bf16 v[84:87], v[68:71], v[12:15], v[84:87]
	v_fmamk_f32 v72, v72, 0x3e38aa3b, v36
	v_fmamk_f32 v73, v73, 0x3e38aa3b, v37
	v_fmamk_f32 v74, v74, 0x3e38aa3b, v38
	v_fmamk_f32 v75, v75, 0x3e38aa3b, v39
	v_mfma_f32_16x16x32_bf16 v[88:91], v[56:59], v[8:11], v[228:231]
	v_mfma_f32_16x16x32_bf16 v[88:91], v[60:63], v[12:15], v[88:91]
	v_fmamk_f32 v76, v76, 0x3e38aa3b, v32
	v_fmamk_f32 v77, v77, 0x3e38aa3b, v33
	v_fmamk_f32 v78, v78, 0x3e38aa3b, v34
	v_fmamk_f32 v79, v79, 0x3e38aa3b, v35
	v_mfma_f32_16x16x32_bf16 v[92:95], v[48:51], v[8:11], v[228:231]
	v_mfma_f32_16x16x32_bf16 v[92:95], v[52:55], v[12:15], v[92:95]
	v_fmamk_f32 v80, v80, 0x3e38aa3b, v28
	v_fmamk_f32 v81, v81, 0x3e38aa3b, v29
	v_fmamk_f32 v82, v82, 0x3e38aa3b, v30
	v_fmamk_f32 v83, v83, 0x3e38aa3b, v31
	v_mfma_f32_16x16x32_bf16 v[164:167], v[40:43], v[8:11], v[228:231]
	v_mfma_f32_16x16x32_bf16 v[164:167], v[44:47], v[12:15], v[164:167]
	v_fmamk_f32 v96, v96, 0x3e38aa3b, v24
	v_fmamk_f32 v97, v97, 0x3e38aa3b, v25
	v_fmamk_f32 v98, v98, 0x3e38aa3b, v26
	v_fmamk_f32 v99, v99, 0x3e38aa3b, v27
	ds_read_b64_tr_b16 v[68:69], v221 offset:9216
	ds_read_b64_tr_b16 v[60:61], v221 offset:9248
	ds_read_b64_tr_b16 v[64:65], v221 offset:9280
	ds_read_b64_tr_b16 v[56:57], v221 offset:9312
	ds_read_b64_tr_b16 v[70:71], v221 offset:11520
	ds_read_b64_tr_b16 v[62:63], v221 offset:11552
	ds_read_b64_tr_b16 v[66:67], v221 offset:11584
	ds_read_b64_tr_b16 v[58:59], v221 offset:11616
	ds_read_b64_tr_b16 v[52:53], v221 offset:13824
	ds_read_b64_tr_b16 v[48:49], v221 offset:13856
	ds_read_b64_tr_b16 v[44:45], v221 offset:13888
	ds_read_b64_tr_b16 v[40:41], v221 offset:13920
	ds_read_b64_tr_b16 v[54:55], v221 offset:16128
	ds_read_b64_tr_b16 v[50:51], v221 offset:16160
	ds_read_b64_tr_b16 v[46:47], v221 offset:16192
	ds_read_b64_tr_b16 v[42:43], v221 offset:16224
	v_cmp_ge_i32_e32 vcc, 0, v172
	v_cmp_ge_i32_e64 s[4:5], -1, v172
	v_cmp_ge_i32_e64 s[100:101], -2, v172
	v_cndmask_b32_e32 v72, v200, v72, vcc
	v_cndmask_b32_e64 v73, v200, v73, s[4:5]
	v_cndmask_b32_e64 v74, v200, v74, s[100:101]
	v_cmp_ge_i32_e32 vcc, -3, v172
	v_cmp_ge_i32_e64 s[4:5], 0, v173
	v_cmp_ge_i32_e64 s[100:101], -1, v173
	v_cndmask_b32_e32 v75, v200, v75, vcc
	v_cndmask_b32_e64 v76, v200, v76, s[4:5]
	v_cndmask_b32_e64 v77, v200, v77, s[100:101]
	v_cmp_ge_i32_e32 vcc, -2, v173
	v_cmp_ge_i32_e64 s[4:5], -3, v173
	v_cmp_ge_i32_e64 s[100:101], 0, v174
	v_cndmask_b32_e32 v78, v200, v78, vcc
	v_cndmask_b32_e64 v79, v200, v79, s[4:5]
	v_cndmask_b32_e64 v80, v200, v80, s[100:101]
; DI unsigned pk2(float lo, float hi) { unsigned r; asm volatile("v_cvt_pk_bf16_f32 %0, %1, %2" : "=v"(r) : "v"(lo), "v"(hi)); return r; }
; DI float ex2(float x) { return __builtin_amdgcn_exp2f(x); }
; DI float shx(float v, int m, int lane) { return __int_as_float(__builtin_amdgcn_ds_bpermute((lane ^ m) << 2, __float_as_int(v))); }
; template <bool DIAG>
; DI void fox_tile(const bf16_t* sK, const bf16_t* sV, const float* sFk, const bf16x8 (&qf)[2][2], f32x4 (&o)[2][4], float (&mrun)[2], float (&lsum)[2], int key0, int qg0, int fr, int fq, int lane) {
;     ...
;         float x = __builtin_fmaf(s[mi][t][j], SC2, fk[t][j]);
;         if (DIAG) { if (key0 + 16 * t + 4 * fq + j > qg0 + 16 * mi) x = -INFINITY; }
;         s[mi][t][j] = x; mx = fmaxf(mx, x);
;       }
;     mx = fmaxf(mx, shx(mx, 16, lane)); mx = fmaxf(mx, shx(mx, 32, lane));
;     const float mnew = fmaxf(mrun[mi], mx), alpha = ex2(mrun[mi] - mnew);
;     mrun[mi] = mnew;
;     float ps = 0.f;
; #pragma unroll
;     for (int t = 0; t < 4; ++t)
; #pragma unroll
;       for (int j = 0; j < 4; ++j) { const float pv = ex2(s[mi][t][j] - mnew); s[mi][t][j] = pv; ps += pv; }
;     lsum[mi] = lsum[mi] * alpha + ps;
; #pragma unroll
;     for (int d = 0; d < 4; ++d) o[mi][d] *= alpha;
;   }
; #pragma unroll
;   for (int k2 = 0; k2 < 2; ++k2) {
;     bf16x8 pa[2];
; #pragma unroll
;     for (int mi = 0; mi < 2; ++mi) pa[mi] = mk8(pk2(s[mi][2 * k2][0], s[mi][2 * k2][1]), pk2(s[mi][2 * k2][2], s[mi][2 * k2][3]), pk2(s[mi][2 * k2 + 1][0], s[mi][2 * k2 + 1][1]), pk2(s[mi][2 * k2 + 1][2], s[mi][2 * k2 + 1][3]));
	v_cmp_ge_i32_e32 vcc, -1, v174
	v_cmp_ge_i32_e64 s[4:5], -2, v174
	v_cmp_ge_i32_e64 s[100:101], -3, v174
	v_cndmask_b32_e32 v81, v200, v81, vcc
	v_cndmask_b32_e64 v82, v200, v82, s[4:5]
	v_cndmask_b32_e64 v83, v200, v83, s[100:101]
	v_cmp_ge_i32_e32 vcc, 0, v175
	v_cmp_ge_i32_e64 s[4:5], -1, v175
	v_cmp_ge_i32_e64 s[100:101], -2, v175
	v_cndmask_b32_e32 v96, v200, v96, vcc
	v_cndmask_b32_e64 v97, v200, v97, s[4:5]
	v_cndmask_b32_e64 v98, v200, v98, s[100:101]
	v_cmp_ge_i32_e32 vcc, -3, v175
	s_nop 1
	v_cndmask_b32_e32 v99, v200, v99, vcc
	v_exp_f32_e32 v72, v72
	v_exp_f32_e32 v73, v73
	v_exp_f32_e32 v74, v74
	v_exp_f32_e32 v75, v75
	v_exp_f32_e32 v76, v76
	v_exp_f32_e32 v77, v77
	v_exp_f32_e32 v78, v78
	v_exp_f32_e32 v79, v79
	v_exp_f32_e32 v80, v80
	v_exp_f32_e32 v81, v81
	v_exp_f32_e32 v82, v82
	v_exp_f32_e32 v83, v83
	v_exp_f32_e32 v96, v96
	v_exp_f32_e32 v97, v97
	v_exp_f32_e32 v98, v98
	v_exp_f32_e32 v99, v99
	v_fmamk_f32 v84, v84, 0x3e38aa3b, v36
	v_fmamk_f32 v85, v85, 0x3e38aa3b, v37
	v_fmamk_f32 v86, v86, 0x3e38aa3b, v38
	v_fmamk_f32 v87, v87, 0x3e38aa3b, v39
	v_fmamk_f32 v88, v88, 0x3e38aa3b, v32
	v_fmamk_f32 v89, v89, 0x3e38aa3b, v33
	v_fmamk_f32 v90, v90, 0x3e38aa3b, v34
	v_fmamk_f32 v91, v91, 0x3e38aa3b, v35
	v_fmamk_f32 v92, v92, 0x3e38aa3b, v28
	v_fmamk_f32 v93, v93, 0x3e38aa3b, v29
	v_fmamk_f32 v94, v94, 0x3e38aa3b, v30
	v_fmamk_f32 v95, v95, 0x3e38aa3b, v31
	v_fmamk_f32 v164, v164, 0x3e38aa3b, v24
	v_fmamk_f32 v165, v165, 0x3e38aa3b, v25
	v_fmamk_f32 v166, v166, 0x3e38aa3b, v26
	v_fmamk_f32 v167, v167, 0x3e38aa3b, v27
	v_cmp_ge_i32_e32 vcc, 0, v176
	v_cmp_ge_i32_e64 s[4:5], -1, v176
	v_cmp_ge_i32_e64 s[100:101], -2, v176
	v_cndmask_b32_e32 v84, v200, v84, vcc
	v_cndmask_b32_e64 v85, v200, v85, s[4:5]
	v_cndmask_b32_e64 v86, v200, v86, s[100:101]
	v_cmp_ge_i32_e32 vcc, -3, v176
	v_cmp_ge_i32_e64 s[4:5], 0, v177
	v_cmp_ge_i32_e64 s[100:101], -1, v177
	v_cndmask_b32_e32 v87, v200, v87, vcc
	v_cndmask_b32_e64 v88, v200, v88, s[4:5]
	v_cndmask_b32_e64 v89, v200, v89, s[100:101]
	v_cmp_ge_i32_e32 vcc, -2, v177
	v_cmp_ge_i32_e64 s[4:5], -3, v177
	v_cmp_ge_i32_e64 s[100:101], 0, v178
	v_cndmask_b32_e32 v90, v200, v90, vcc
	v_cndmask_b32_e64 v91, v200, v91, s[4:5]
	v_cndmask_b32_e64 v92, v200, v92, s[100:101]
	v_cmp_ge_i32_e32 vcc, -1, v178
	v_cmp_ge_i32_e64 s[4:5], -2, v178
	v_cmp_ge_i32_e64 s[100:101], -3, v178
	v_cndmask_b32_e32 v93, v200, v93, vcc
	v_cndmask_b32_e64 v94, v200, v94, s[4:5]
	v_cndmask_b32_e64 v95, v200, v95, s[100:101]
	v_cmp_ge_i32_e32 vcc, 0, v179
	v_cmp_ge_i32_e64 s[4:5], -1, v179
	v_cmp_ge_i32_e64 s[100:101], -2, v179
	v_cndmask_b32_e32 v164, v200, v164, vcc
	v_cndmask_b32_e64 v165, v200, v165, s[4:5]
	v_cndmask_b32_e64 v166, v200, v166, s[100:101]
	v_cmp_ge_i32_e32 vcc, -3, v179
	s_nop 1
	v_cndmask_b32_e32 v167, v200, v167, vcc
	v_pk_add_f32 v[146:147], v[72:73], v[74:75]
	v_pk_add_f32 v[148:149], v[76:77], v[78:79]
	v_pk_add_f32 v[150:151], v[80:81], v[82:83]
	v_pk_add_f32 v[152:153], v[96:97], v[98:99]
	v_pk_add_f32 v[146:147], v[146:147], v[148:149]
	v_pk_add_f32 v[150:151], v[150:151], v[152:153]
	v_pk_add_f32 v[146:147], v[146:147], v[150:151]
	v_add_f32_e32 v146, v146, v147
	v_exp_f32_e32 v84, v84
	v_exp_f32_e32 v85, v85
	v_exp_f32_e32 v86, v86
	v_exp_f32_e32 v87, v87
	v_exp_f32_e32 v88, v88
	v_exp_f32_e32 v89, v89
	v_exp_f32_e32 v90, v90
	v_exp_f32_e32 v91, v91
	v_exp_f32_e32 v92, v92
	v_exp_f32_e32 v93, v93
	v_exp_f32_e32 v94, v94
	v_exp_f32_e32 v95, v95
	v_exp_f32_e32 v164, v164
	v_exp_f32_e32 v165, v165
	v_exp_f32_e32 v166, v166
	v_exp_f32_e32 v167, v167
	v_pk_add_f32 v[148:149], v[84:85], v[86:87]
	v_pk_add_f32 v[150:151], v[88:89], v[90:91]
	v_pk_add_f32 v[152:153], v[92:93], v[94:95]
	v_pk_add_f32 v[154:155], v[164:165], v[166:167]
	v_pk_add_f32 v[148:149], v[148:149], v[150:151]
	v_pk_add_f32 v[152:153], v[152:153], v[154:155]
	v_pk_add_f32 v[148:149], v[148:149], v[152:153]
	v_add_f32_e32 v148, v148, v149
	v_max_f32_e32 v147, v146, v148
	v_cmp_lt_f32_e32 vcc, 0x69800000, v147
	s_cbranch_vccnz .Lfox2_dfallback
	v_add_f32_e32 v128, v128, v146
	v_add_f32_e32 v129, v129, v148
	v_cvt_pk_bf16_f32 v36, v72, v73
	v_cvt_pk_bf16_f32 v37, v74, v75
	v_cvt_pk_bf16_f32 v38, v76, v77
	v_cvt_pk_bf16_f32 v39, v78, v79
	v_cvt_pk_bf16_f32 v28, v80, v81
	v_cvt_pk_bf16_f32 v29, v82, v83
	v_cvt_pk_bf16_f32 v30, v96, v97
	v_cvt_pk_bf16_f32 v31, v98, v99
	s_cmp_eq_u32 s99, 0
	s_cbranch_scc1 .Lfox2_nm4
	s_barrier
